# P4 pass header: gate loads stay in flight across the pass's first interval (vmcnt(2), loop entered behind its vmcnt(0))
# baseline (speedup 1.0000x reference)
.LBB0_640:
	v_mov_b32_e32 v178, v184
	v_mov_b32_e32 v179, v182
	s_cmp_gt_i32 s68, s69
	.p2align 8
	s_cbranch_scc1 .LBB0_681
	v_mov_b32_e32 v86, v84
	v_mov_b32_e32 v87, v84
	v_mov_b32_e32 v88, v84
	v_mov_b32_e32 v89, v84
	v_mov_b32_e32 v90, v84
	v_mov_b32_e32 v91, v84
	v_mov_b32_e32 v92, v84
	v_mov_b32_e32 v93, v84
	v_mov_b32_e32 v94, v84
	v_mov_b32_e32 v95, v84
	v_mov_b32_e32 v96, v84
	v_mov_b32_e32 v97, v84
	v_mov_b32_e32 v98, v84
	v_mov_b32_e32 v99, v84
	v_mov_b32_e32 v16, v2
	v_mov_b32_e32 v17, v2
	v_mov_b32_e32 v85, v84
	s_cmp_eq_u32 s11, s61
	v_mov_b32_e32 v3, v2
	v_mov_b32_e32 v4, v2
	v_mov_b32_e32 v5, v2
	v_mov_b32_e32 v6, v2
	v_mov_b32_e32 v7, v2
	v_mov_b32_e32 v8, v2
	v_mov_b32_e32 v9, v2
	v_mov_b32_e32 v10, v2
	v_mov_b32_e32 v11, v2
	v_mov_b32_e32 v12, v2
	v_mov_b32_e32 v13, v2
	v_mov_b32_e32 v14, v2
	v_mov_b32_e32 v15, v2
	v_mov_b32_e32 v181, 0
	v_mov_b64_e32 v[100:101], v[98:99]
	v_mov_b64_e32 v[82:83], v[16:17]
	v_mov_b64_e32 v[66:67], v[16:17]
	s_cselect_b64 s[34:35], -1, 0
	s_add_i32 s74, s21, 0
	s_add_i32 s75, s38, 0
	v_mov_b32_e32 v186, v184
	v_mov_b32_e32 v187, v184
	v_mov_b32_e32 v188, v182
	v_mov_b32_e32 v189, v182
	v_mov_b32_e32 v20, v2
	v_mov_b32_e32 v21, v2
	v_mov_b32_e32 v22, v2
	v_mov_b32_e32 v23, v2
	v_mov_b32_e32 v24, v2
	v_mov_b32_e32 v25, v2
	v_mov_b32_e32 v26, v2
	v_mov_b32_e32 v27, v2
	v_mov_b32_e32 v28, v2
	v_mov_b32_e32 v29, v2
	v_mov_b32_e32 v30, v2
	v_mov_b32_e32 v31, v2
	v_mov_b32_e32 v32, v2
	v_mov_b32_e32 v33, v2
	v_mov_b32_e32 v34, v2
	v_mov_b32_e32 v35, v2
	v_mov_b32_e32 v36, v2
	v_mov_b32_e32 v37, v2
	v_mov_b32_e32 v38, v2
	v_mov_b32_e32 v39, v2
	v_mov_b32_e32 v40, v2
	v_mov_b32_e32 v41, v2
	v_mov_b32_e32 v42, v2
	v_mov_b32_e32 v43, v2
	v_mov_b32_e32 v44, v2
	v_mov_b32_e32 v45, v2
	v_mov_b32_e32 v46, v2
	v_mov_b32_e32 v47, v2
	v_mov_b32_e32 v48, v2
	v_mov_b32_e32 v49, v2
	v_mov_b32_e32 v50, v2
	v_mov_b32_e32 v51, v2
	v_mov_b32_e32 v180, v181
	v_mov_b64_e32 v[98:99], v[96:97]
	v_mov_b64_e32 v[96:97], v[94:95]
	v_mov_b64_e32 v[94:95], v[92:93]
	v_mov_b64_e32 v[92:93], v[90:91]
	v_mov_b64_e32 v[90:91], v[88:89]
	v_mov_b64_e32 v[88:89], v[86:87]
	v_mov_b64_e32 v[86:87], v[84:85]
	v_mov_b64_e32 v[80:81], v[14:15]
	v_mov_b64_e32 v[78:79], v[12:13]
	v_mov_b64_e32 v[76:77], v[10:11]
	v_mov_b64_e32 v[74:75], v[8:9]
	v_mov_b64_e32 v[72:73], v[6:7]
	v_mov_b64_e32 v[70:71], v[4:5]
	v_mov_b64_e32 v[68:69], v[2:3]
	v_mov_b64_e32 v[64:65], v[14:15]
	v_mov_b64_e32 v[62:63], v[12:13]
	v_mov_b64_e32 v[60:61], v[10:11]
	v_mov_b64_e32 v[58:59], v[8:9]
	v_mov_b64_e32 v[56:57], v[6:7]
	v_mov_b64_e32 v[54:55], v[4:5]
	v_mov_b64_e32 v[52:53], v[2:3]
	s_and_b64 vcc, exec, s[4:5]
	s_cbranch_vccnz .Lhw0
	s_waitcnt vmcnt(2)
	s_branch .Lit_bar
.Lhw0:
	s_waitcnt vmcnt(0)
	s_branch .Lit_bar

.Lit_bar:
	s_barrier
	v_cmp_le_i32_e32 vcc, s43, v197
	s_cbranch_vccnz .LBB0_648
	s_cmp_eq_u32 s48, 1
	s_cselect_b32 s0, s12, s16
	s_cselect_b32 s1, s13, s17
	s_cselect_b32 s21, s14, s18
	s_cselect_b32 s38, s15, s19
	s_cmp_eq_u32 s48, 0
	s_cselect_b32 s39, s7, s1
	s_cselect_b32 s40, s6, s0
	s_cselect_b32 s76, s9, s38
	s_cselect_b32 s77, s8, s21
	s_cselect_b32 s38, s42, s45
	s_lshl_b32 s0, s49, 15
	s_and_b32 s0, s0, 0x8000
	s_ashr_i32 s21, s20, 31
	s_add_i32 s41, s46, s0
	s_lshl_b64 s[0:1], s[20:21], 13
	s_add_u32 s78, s40, s0
	s_addc_u32 s79, s39, s1
	s_mov_b32 m0, s41
	s_nop 0
	global_load_lds_dwordx4 v166, s[78:79]
	s_add_u32 s78, s77, s0
	s_addc_u32 s79, s76, s1
	s_add_i32 m0, s41, 0x2000
	s_nop 0
	global_load_lds_dwordx4 v168, s[78:79]
	s_cmp_ge_i32 s20, s38
	s_cbranch_scc1 .LBB0_646
	s_add_u32 s0, s0, 0x2000
	s_addc_u32 s1, s1, 0
	s_add_u32 s78, s40, s0
	s_addc_u32 s79, s39, s1
	s_add_i32 m0, s41, 0x4000
	s_nop 0
	global_load_lds_dwordx4 v166, s[78:79]
	s_add_u32 s78, s77, s0
	s_addc_u32 s79, s76, s1
	s_add_i32 m0, s41, 0x6000
	s_nop 0
	global_load_lds_dwordx4 v168, s[78:79]
